# layer-1 weight transposes split retuned: high half takes items [0,7344), low half [7344,9392) after its context unit
# speedup vs baseline: 1.0041x; 1.0041x over previous
.LBB0_522:
	s_andn2_b64 vcc, exec, s[36:37]
	s_cbranch_vccnz .LBB0_548
	s_lshr_b32 s2, s18, 31
	s_add_i32 s2, s18, s2
	s_ashr_i32 s2, s2, 1
	s_cmp_lt_i32 s20, s2
	s_cbranch_scc1 .Ltr_low
	s_sub_i32 s3, s20, s2
	s_mov_b32 s9, 0
	s_movk_i32 s83, 0x1caf
	s_branch .Ltr_go
.Ltr_low:
	s_mov_b32 s3, s20
	s_movk_i32 s9, 0x1cb0
	s_sub_i32 s2, s18, s2
